# plus: fold the remaining 45 canonicalising v_max into the relu max in the relu-squared epilogue
# baseline (speedup 1.0000x reference)
; __device__ __forceinline__ unsigned pkbf(float lo, float hi) { f32x2p v = {lo, hi}; bf16x2p b = __builtin_convertvector(v, bf16x2p); return __builtin_bit_cast(unsigned, b); }
;     __device__ __forceinline__ void operator()(const f32x4 (&acc)[2][2][4][2], const Unit& u, int wr, int wc, int fr, int fq) const {
;     ...
;                         if constexpr (MODE == EPI_RELU2) {
; #pragma unroll
;                             for (int e = 0; e < 4; ++e) { float a = fmaxf(v0[e], 0.f), b = fmaxf(v1[e], 0.f); v0[e] = a * a; v1[e] = b * b; }
;                         }
;                         if constexpr (MODE == EPI_GATEMUL) {
;                             const u32x4 gw = *(const u32x4*)(G + off); v0 = v0 * bscale; v1 = v1 * bscale;
;                             v0[0] *= bflo(gw.x); v0[1] *= bfhi(gw.x); v0[2] *= bflo(gw.y); v0[3] *= bfhi(gw.y);
;                             v1[0] *= bflo(gw.z); v1[1] *= bfhi(gw.z); v1[2] *= bflo(gw.w); v1[3] *= bfhi(gw.w);
;                             if (!first) {
;                                 const u32x4 ow = *(const u32x4*)(O + off);
;                                 v0[0] += bflo(ow.x); v0[1] += bfhi(ow.x); v0[2] += bflo(ow.y); v0[3] += bfhi(ow.y);
;                                 v1[0] += bflo(ow.z); v1[1] += bfhi(ow.z); v1[2] += bflo(ow.w); v1[3] += bfhi(ow.w);
;                             }
;                         }
;                         u32x4 w; w.x = pkbf(v0[0], v0[1]); w.y = pkbf(v0[2], v0[3]); w.z = pkbf(v1[0], v1[1]); w.w = pkbf(v1[2], v1[3]);
;                         *(u32x4*)(O + off) = w;
.LBB0_859:
	v_lshl_add_u32 v130, s57, 8, v160
	v_max_f32_e32 v126, 0, v126
	v_max_f32_e32 v122, 0, v122
	v_max_f32_e32 v127, 0, v127
	v_max_f32_e32 v123, 0, v123
	v_lshl_or_b32 v132, s56, 8, v162
	v_ashrrev_i32_e32 v131, 31, v130
	v_pk_mul_f32 v[126:127], v[126:127], v[126:127]
	v_pk_mul_f32 v[122:123], v[122:123], v[122:123]
	v_max_f32_e32 v128, 0, v128
	v_max_f32_e32 v124, 0, v124
	v_max_f32_e32 v129, 0, v129
	v_max_f32_e32 v125, 0, v125
	v_ashrrev_i32_e32 v133, 31, v132
	v_pk_mul_f32 v[128:129], v[128:129], v[128:129]
	v_pk_mul_f32 v[164:165], v[124:125], v[124:125]
	v_cvt_pk_bf16_f32 v124, v126, v127
	v_cvt_pk_bf16_f32 v126, v122, v123
	v_lshlrev_b64 v[122:123], 13, v[130:131]
	v_cvt_pk_bf16_f32 v125, v128, v129
	v_lshl_add_u64 v[122:123], s[24:25], 0, v[122:123]
	v_lshlrev_b64 v[128:129], 1, v[132:133]
	v_cvt_pk_bf16_f32 v127, v164, v165
	v_lshl_add_u64 v[122:123], v[122:123], 0, v[128:129]
	v_max_f32_e32 v114, 0, v114
	v_max_f32_e32 v115, 0, v115
	global_store_dwordx4 v[122:123], v[124:127], off
	s_nop 1
	v_pk_mul_f32 v[124:125], v[114:115], v[114:115]
	v_max_f32_e32 v116, 0, v116
	v_max_f32_e32 v118, 0, v118
	v_max_f32_e32 v119, 0, v119
	v_max_f32_e32 v114, 0, v120
	v_max_f32_e32 v115, 0, v121
	v_max_f32_e32 v117, 0, v117
	v_pk_mul_f32 v[118:119], v[118:119], v[118:119]
	v_pk_mul_f32 v[120:121], v[114:115], v[114:115]
	v_pk_mul_f32 v[126:127], v[116:117], v[116:117]
	v_cvt_pk_bf16_f32 v114, v118, v119
	v_cvt_pk_bf16_f32 v115, v120, v121
	v_cvt_pk_bf16_f32 v116, v124, v125
	v_cvt_pk_bf16_f32 v117, v126, v127
	v_max_f32_e32 v106, 0, v106
	v_max_f32_e32 v107, 0, v107
	global_store_dwordx4 v[122:123], v[114:117], off offset:256
	s_nop 1
	v_pk_mul_f32 v[116:117], v[106:107], v[106:107]
	v_or_b32_e32 v114, 16, v130
	v_max_f32_e32 v110, 0, v110
	v_max_f32_e32 v111, 0, v111
	v_max_f32_e32 v108, 0, v108
	v_ashrrev_i32_e32 v115, 31, v114
	v_pk_mul_f32 v[110:111], v[110:111], v[110:111]
	v_max_f32_e32 v106, 0, v112
	v_max_f32_e32 v107, 0, v113
	v_max_f32_e32 v109, 0, v109
	v_pk_mul_f32 v[112:113], v[106:107], v[106:107]
	v_cvt_pk_bf16_f32 v106, v110, v111
	v_lshlrev_b64 v[110:111], 13, v[114:115]
	v_pk_mul_f32 v[118:119], v[108:109], v[108:109]
	v_lshl_add_u64 v[110:111], s[24:25], 0, v[110:111]
	v_cvt_pk_bf16_f32 v107, v112, v113
	v_cvt_pk_bf16_f32 v108, v116, v117
	v_cvt_pk_bf16_f32 v109, v118, v119
	v_lshl_add_u64 v[110:111], v[110:111], 0, v[128:129]
	v_max_f32_e32 v98, 0, v98
	v_max_f32_e32 v99, 0, v99
	global_store_dwordx4 v[110:111], v[106:109], off
	s_nop 1
	v_pk_mul_f32 v[106:107], v[98:99], v[98:99]
	v_max_f32_e32 v100, 0, v100
	v_max_f32_e32 v102, 0, v102
	v_max_f32_e32 v103, 0, v103
	v_max_f32_e32 v98, 0, v104
	v_max_f32_e32 v99, 0, v105
	v_max_f32_e32 v101, 0, v101
	v_pk_mul_f32 v[102:103], v[102:103], v[102:103]
	v_pk_mul_f32 v[104:105], v[98:99], v[98:99]
	v_pk_mul_f32 v[108:109], v[100:101], v[100:101]
	v_cvt_pk_bf16_f32 v98, v102, v103
	v_cvt_pk_bf16_f32 v99, v104, v105
	v_cvt_pk_bf16_f32 v100, v106, v107
	v_cvt_pk_bf16_f32 v101, v108, v109
	v_max_f32_e32 v90, 0, v90
	v_max_f32_e32 v91, 0, v91
	global_store_dwordx4 v[110:111], v[98:101], off offset:256
	s_nop 1
	v_pk_mul_f32 v[100:101], v[90:91], v[90:91]
	v_or_b32_e32 v98, 32, v130
	v_max_f32_e32 v94, 0, v94
	v_max_f32_e32 v95, 0, v95
	v_max_f32_e32 v92, 0, v92
	v_ashrrev_i32_e32 v99, 31, v98
	v_pk_mul_f32 v[94:95], v[94:95], v[94:95]
	v_max_f32_e32 v90, 0, v96
	v_max_f32_e32 v91, 0, v97
	v_max_f32_e32 v93, 0, v93
	v_pk_mul_f32 v[96:97], v[90:91], v[90:91]
	v_cvt_pk_bf16_f32 v90, v94, v95
	v_lshlrev_b64 v[94:95], 13, v[98:99]
	v_pk_mul_f32 v[102:103], v[92:93], v[92:93]
	v_lshl_add_u64 v[94:95], s[24:25], 0, v[94:95]
	v_cvt_pk_bf16_f32 v91, v96, v97
	v_cvt_pk_bf16_f32 v92, v100, v101
	v_cvt_pk_bf16_f32 v93, v102, v103
	v_lshl_add_u64 v[94:95], v[94:95], 0, v[128:129]
	v_max_f32_e32 v82, 0, v82
	v_max_f32_e32 v83, 0, v83
	global_store_dwordx4 v[94:95], v[90:93], off
	s_nop 1
	v_pk_mul_f32 v[90:91], v[82:83], v[82:83]
	v_max_f32_e32 v84, 0, v84
	v_max_f32_e32 v86, 0, v86
	v_max_f32_e32 v87, 0, v87
	v_max_f32_e32 v82, 0, v88
	v_max_f32_e32 v83, 0, v89
	v_max_f32_e32 v85, 0, v85
	v_pk_mul_f32 v[86:87], v[86:87], v[86:87]
	v_pk_mul_f32 v[88:89], v[82:83], v[82:83]
	v_pk_mul_f32 v[92:93], v[84:85], v[84:85]
	v_cvt_pk_bf16_f32 v82, v86, v87
	v_cvt_pk_bf16_f32 v83, v88, v89
	v_cvt_pk_bf16_f32 v84, v90, v91
	v_cvt_pk_bf16_f32 v85, v92, v93
	v_max_f32_e32 v74, 0, v74
	v_max_f32_e32 v75, 0, v75
	global_store_dwordx4 v[94:95], v[82:85], off offset:256
	s_nop 1
	v_pk_mul_f32 v[84:85], v[74:75], v[74:75]
	v_or_b32_e32 v82, 48, v130
	v_max_f32_e32 v78, 0, v78
	v_max_f32_e32 v79, 0, v79
	v_max_f32_e32 v76, 0, v76
	v_ashrrev_i32_e32 v83, 31, v82
	v_pk_mul_f32 v[78:79], v[78:79], v[78:79]
	v_max_f32_e32 v74, 0, v80
	v_max_f32_e32 v75, 0, v81
	v_max_f32_e32 v77, 0, v77
	v_pk_mul_f32 v[80:81], v[74:75], v[74:75]
	v_cvt_pk_bf16_f32 v74, v78, v79
	v_lshlrev_b64 v[78:79], 13, v[82:83]
	v_pk_mul_f32 v[86:87], v[76:77], v[76:77]
	v_lshl_add_u64 v[78:79], s[24:25], 0, v[78:79]
	v_cvt_pk_bf16_f32 v75, v80, v81
	v_cvt_pk_bf16_f32 v76, v84, v85
	v_cvt_pk_bf16_f32 v77, v86, v87
	v_lshl_add_u64 v[78:79], v[78:79], 0, v[128:129]
	v_max_f32_e32 v66, 0, v66
	v_max_f32_e32 v67, 0, v67
	global_store_dwordx4 v[78:79], v[74:77], off
	s_nop 1
	v_pk_mul_f32 v[74:75], v[66:67], v[66:67]
	v_max_f32_e32 v68, 0, v68
	v_max_f32_e32 v70, 0, v70
	v_max_f32_e32 v71, 0, v71
	v_max_f32_e32 v66, 0, v72
	v_max_f32_e32 v67, 0, v73
	v_max_f32_e32 v69, 0, v69
	v_pk_mul_f32 v[70:71], v[70:71], v[70:71]
	v_pk_mul_f32 v[72:73], v[66:67], v[66:67]
	v_pk_mul_f32 v[76:77], v[68:69], v[68:69]
	v_cvt_pk_bf16_f32 v66, v70, v71
; __device__ __forceinline__ unsigned pkbf(float lo, float hi) { f32x2p v = {lo, hi}; bf16x2p b = __builtin_convertvector(v, bf16x2p); return __builtin_bit_cast(unsigned, b); }
;     __device__ __forceinline__ void operator()(const f32x4 (&acc)[2][2][4][2], const Unit& u, int wr, int wc, int fr, int fq) const {
;     ...
;                         if constexpr (MODE == EPI_RELU2) {
; #pragma unroll
;                             for (int e = 0; e < 4; ++e) { float a = fmaxf(v0[e], 0.f), b = fmaxf(v1[e], 0.f); v0[e] = a * a; v1[e] = b * b; }
;                         }
;                         if constexpr (MODE == EPI_GATEMUL) {
;                             const u32x4 gw = *(const u32x4*)(G + off); v0 = v0 * bscale; v1 = v1 * bscale;
;                             v0[0] *= bflo(gw.x); v0[1] *= bfhi(gw.x); v0[2] *= bflo(gw.y); v0[3] *= bfhi(gw.y);
;                             v1[0] *= bflo(gw.z); v1[1] *= bfhi(gw.z); v1[2] *= bflo(gw.w); v1[3] *= bfhi(gw.w);
;                             if (!first) {
;                                 const u32x4 ow = *(const u32x4*)(O + off);
;                                 v0[0] += bflo(ow.x); v0[1] += bfhi(ow.x); v0[2] += bflo(ow.y); v0[3] += bfhi(ow.y);
;                                 v1[0] += bflo(ow.z); v1[1] += bfhi(ow.z); v1[2] += bflo(ow.w); v1[3] += bfhi(ow.w);
;                             }
;                         }
;                         u32x4 w; w.x = pkbf(v0[0], v0[1]); w.y = pkbf(v0[2], v0[3]); w.z = pkbf(v1[0], v1[1]); w.w = pkbf(v1[2], v1[3]);
;                         *(u32x4*)(O + off) = w;
	v_cvt_pk_bf16_f32 v67, v72, v73
	v_cvt_pk_bf16_f32 v68, v74, v75
	v_cvt_pk_bf16_f32 v69, v76, v77
	v_max_f32_e32 v58, 0, v58
	v_max_f32_e32 v59, 0, v59
	global_store_dwordx4 v[78:79], v[66:69], off offset:256
	s_nop 1
	v_pk_mul_f32 v[66:67], v[58:59], v[58:59]
	v_max_f32_e32 v60, 0, v60
	v_max_f32_e32 v58, 0, v64
	v_max_f32_e32 v59, 0, v65
	v_max_f32_e32 v62, 0, v62
	v_max_f32_e32 v63, 0, v63
	v_max_f32_e32 v61, 0, v61
	v_pk_mul_f32 v[64:65], v[58:59], v[58:59]
	s_mov_b32 s4, 0x100000
	v_pk_mul_f32 v[62:63], v[62:63], v[62:63]
	v_pk_mul_f32 v[68:69], v[60:61], v[60:61]
	v_cvt_pk_bf16_f32 v59, v64, v65
	v_add_co_u32_e32 v64, vcc, s4, v122
	v_cvt_pk_bf16_f32 v58, v62, v63
	v_cvt_pk_bf16_f32 v60, v66, v67
	v_cvt_pk_bf16_f32 v61, v68, v69
	v_addc_co_u32_e32 v65, vcc, 0, v123, vcc
	v_max_f32_e32 v50, 0, v50
	v_max_f32_e32 v51, 0, v51
	global_store_dwordx4 v[64:65], v[58:61], off
	s_nop 1
	v_pk_mul_f32 v[58:59], v[50:51], v[50:51]
	v_max_f32_e32 v52, 0, v52
	v_max_f32_e32 v54, 0, v54
	v_max_f32_e32 v55, 0, v55
	v_max_f32_e32 v50, 0, v56
	v_max_f32_e32 v51, 0, v57
	v_max_f32_e32 v53, 0, v53
	s_mov_b64 s[10:11], 0x100000
	v_pk_mul_f32 v[54:55], v[54:55], v[54:55]
	v_pk_mul_f32 v[56:57], v[50:51], v[50:51]
	v_pk_mul_f32 v[60:61], v[52:53], v[52:53]
	v_lshl_add_u64 v[62:63], v[122:123], 0, s[10:11]
	v_cvt_pk_bf16_f32 v50, v54, v55
	v_cvt_pk_bf16_f32 v51, v56, v57
	v_cvt_pk_bf16_f32 v52, v58, v59
	v_cvt_pk_bf16_f32 v53, v60, v61
	v_max_f32_e32 v42, 0, v42
	v_max_f32_e32 v43, 0, v43
	global_store_dwordx4 v[62:63], v[50:53], off offset:256
	s_nop 1
	v_pk_mul_f32 v[50:51], v[42:43], v[42:43]
	v_max_f32_e32 v44, 0, v44
	v_max_f32_e32 v42, 0, v48
	v_max_f32_e32 v43, 0, v49
	v_max_f32_e32 v46, 0, v46
	v_max_f32_e32 v47, 0, v47
	v_max_f32_e32 v45, 0, v45
	v_pk_mul_f32 v[48:49], v[42:43], v[42:43]
	s_mov_b32 s4, 0x120000
	v_pk_mul_f32 v[46:47], v[46:47], v[46:47]
	v_pk_mul_f32 v[52:53], v[44:45], v[44:45]
	v_cvt_pk_bf16_f32 v43, v48, v49
	v_add_co_u32_e32 v48, vcc, s4, v122
	v_cvt_pk_bf16_f32 v42, v46, v47
	v_cvt_pk_bf16_f32 v44, v50, v51
	v_cvt_pk_bf16_f32 v45, v52, v53
	v_addc_co_u32_e32 v49, vcc, 0, v123, vcc
	v_max_f32_e32 v34, 0, v34
	v_max_f32_e32 v35, 0, v35
	global_store_dwordx4 v[48:49], v[42:45], off
	s_nop 1
	v_pk_mul_f32 v[42:43], v[34:35], v[34:35]
	v_max_f32_e32 v36, 0, v36
	v_max_f32_e32 v38, 0, v38
	v_max_f32_e32 v39, 0, v39
	v_max_f32_e32 v34, 0, v40
	v_max_f32_e32 v35, 0, v41
	v_max_f32_e32 v37, 0, v37
	s_mov_b64 s[10:11], 0x120000
	v_pk_mul_f32 v[38:39], v[38:39], v[38:39]
	v_pk_mul_f32 v[40:41], v[34:35], v[34:35]
	v_pk_mul_f32 v[44:45], v[36:37], v[36:37]
	v_lshl_add_u64 v[46:47], v[122:123], 0, s[10:11]
	v_cvt_pk_bf16_f32 v34, v38, v39
	v_cvt_pk_bf16_f32 v35, v40, v41
	v_cvt_pk_bf16_f32 v36, v42, v43
	v_cvt_pk_bf16_f32 v37, v44, v45
	v_max_f32_e32 v26, 0, v26
	v_max_f32_e32 v27, 0, v27
	global_store_dwordx4 v[46:47], v[34:37], off offset:256
	s_nop 1
	v_pk_mul_f32 v[34:35], v[26:27], v[26:27]
	v_max_f32_e32 v28, 0, v28
	v_max_f32_e32 v26, 0, v32
	v_max_f32_e32 v27, 0, v33
	v_max_f32_e32 v30, 0, v30
	v_max_f32_e32 v31, 0, v31
	v_max_f32_e32 v29, 0, v29
	v_pk_mul_f32 v[32:33], v[26:27], v[26:27]
	s_mov_b32 s4, 0x140000
	v_pk_mul_f32 v[30:31], v[30:31], v[30:31]
	v_pk_mul_f32 v[36:37], v[28:29], v[28:29]
	v_cvt_pk_bf16_f32 v27, v32, v33
	v_add_co_u32_e32 v32, vcc, s4, v122
	v_cvt_pk_bf16_f32 v26, v30, v31
	v_cvt_pk_bf16_f32 v28, v34, v35
	v_cvt_pk_bf16_f32 v29, v36, v37
	v_addc_co_u32_e32 v33, vcc, 0, v123, vcc
	v_max_f32_e32 v18, 0, v18
	v_max_f32_e32 v19, 0, v19
	global_store_dwordx4 v[32:33], v[26:29], off
	s_nop 1
	v_pk_mul_f32 v[26:27], v[18:19], v[18:19]
	v_max_f32_e32 v20, 0, v20
	v_max_f32_e32 v22, 0, v22
	v_max_f32_e32 v23, 0, v23
	v_max_f32_e32 v18, 0, v24
	v_max_f32_e32 v19, 0, v25
	v_max_f32_e32 v21, 0, v21
	s_mov_b64 s[10:11], 0x140000
	v_pk_mul_f32 v[22:23], v[22:23], v[22:23]
	v_pk_mul_f32 v[24:25], v[18:19], v[18:19]
	v_pk_mul_f32 v[28:29], v[20:21], v[20:21]
	v_lshl_add_u64 v[30:31], v[122:123], 0, s[10:11]
	v_cvt_pk_bf16_f32 v18, v22, v23
	v_cvt_pk_bf16_f32 v19, v24, v25
	v_cvt_pk_bf16_f32 v20, v26, v27
	v_cvt_pk_bf16_f32 v21, v28, v29
	v_max_f32_e32 v10, 0, v10
	v_max_f32_e32 v11, 0, v11
	global_store_dwordx4 v[30:31], v[18:21], off offset:256
	s_nop 1
	v_pk_mul_f32 v[18:19], v[10:11], v[10:11]
	v_max_f32_e32 v12, 0, v12
	v_max_f32_e32 v10, 0, v16
	v_max_f32_e32 v11, 0, v17
	v_max_f32_e32 v14, 0, v14
	v_max_f32_e32 v15, 0, v15
	v_max_f32_e32 v13, 0, v13
	v_pk_mul_f32 v[16:17], v[10:11], v[10:11]
	s_mov_b32 s4, 0x160000
	v_pk_mul_f32 v[14:15], v[14:15], v[14:15]
	v_pk_mul_f32 v[20:21], v[12:13], v[12:13]
	v_cvt_pk_bf16_f32 v11, v16, v17
	v_add_co_u32_e32 v16, vcc, s4, v122
	v_cvt_pk_bf16_f32 v10, v14, v15
	v_cvt_pk_bf16_f32 v12, v18, v19
	v_cvt_pk_bf16_f32 v13, v20, v21
	v_addc_co_u32_e32 v17, vcc, 0, v123, vcc
	v_max_f32_e32 v2, 0, v2
	v_max_f32_e32 v3, 0, v3
	global_store_dwordx4 v[16:17], v[10:13], off
	s_nop 1
	v_pk_mul_f32 v[10:11], v[2:3], v[2:3]
	v_max_f32_e32 v4, 0, v4
	v_max_f32_e32 v6, 0, v6
	v_max_f32_e32 v7, 0, v7
	v_max_f32_e32 v2, 0, v8
	v_max_f32_e32 v3, 0, v9
	v_max_f32_e32 v5, 0, v5
	s_mov_b64 s[10:11], 0x160000
	v_pk_mul_f32 v[6:7], v[6:7], v[6:7]
	v_pk_mul_f32 v[8:9], v[2:3], v[2:3]
	v_pk_mul_f32 v[12:13], v[4:5], v[4:5]
	v_lshl_add_u64 v[14:15], v[122:123], 0, s[10:11]
	v_cvt_pk_bf16_f32 v2, v6, v7
	v_cvt_pk_bf16_f32 v3, v8, v9
	v_cvt_pk_bf16_f32 v4, v10, v11
	v_cvt_pk_bf16_f32 v5, v12, v13
	s_andn2_b64 vcc, exec, s[38:39]
	s_mov_b64 s[38:39], -1
	global_store_dwordx4 v[14:15], v[2:5], off offset:256
	s_cbranch_vccnz .LBB0_848
	s_andn2_b64 vcc, exec, s[0:1]
	s_cbranch_vccnz .LBB0_847
	s_barrier
	s_branch .LBB0_847
